# phase0 rebalance: mod_unit workgroups keep 5 of their 13 weight-transpose items, the other 768 items are redistributed to the remaining workgroups
# speedup vs baseline: 1.0268x; 1.0058x over previous
.LBB0_26:
	s_mov_b32 s100, 0
	s_load_dwordx16 s[44:59], s[0:1], 0x80
	v_writelane_b32 v250, s14, 27
	s_add_u32 s64, s90, 0x3240000
	s_addc_u32 s65, s91, 0
	s_add_u32 s30, s90, 0x2c40000
	s_waitcnt lgkmcnt(0)
	v_writelane_b32 v250, s44, 28
	s_addc_u32 s31, s91, 0
	s_add_u32 s66, s90, 0x940000
	v_writelane_b32 v250, s45, 29
	v_writelane_b32 v250, s46, 30
	v_writelane_b32 v250, s47, 31
	v_writelane_b32 v250, s48, 32
	v_writelane_b32 v250, s49, 33
	v_writelane_b32 v250, s50, 34
	v_writelane_b32 v250, s51, 35
	v_writelane_b32 v250, s52, 36
	v_writelane_b32 v250, s53, 37
	v_writelane_b32 v250, s54, 38
	v_writelane_b32 v250, s55, 39
	v_writelane_b32 v250, s56, 40
	v_writelane_b32 v250, s57, 41
	v_writelane_b32 v250, s58, 42
	v_writelane_b32 v250, s59, 43
	s_addc_u32 s67, s91, 0
	v_readlane_b32 s60, v250, 1
	v_lshrrev_b32_e32 v194, 4, v128
	s_cmpk_gt_i32 s19, 0x1a7f
	v_lshrrev_b32_e32 v223, 2, v128
	v_readlane_b32 s61, v250, 2
	s_cbranch_scc1 .LBB0_105
	s_add_i32 s10, s19, 0xffffffa0
	s_cmpk_gt_i32 s19, 0x4ff
	s_cbranch_scc0 .LBB0_33
	s_cmpk_gt_u32 s10, 0x59f
	s_cbranch_scc0 .LBB0_34
	s_cmpk_gt_u32 s10, 0x109f
	s_cbranch_scc0 .LBB0_35
	s_cmpk_gt_u32 s10, 0x161f
	s_cbranch_scc0 .LBB0_36
	s_cmpk_gt_u32 s10, 0x191f
	s_cbranch_scc0 .LBB0_37
	v_readlane_b32 s44, v250, 28
	s_add_i32 s0, s19, 0xffffe680
	v_readlane_b32 s58, v250, 42
	v_readlane_b32 s59, v250, 43
	s_lshr_b32 s16, s0, 4
	s_mov_b64 s[0:1], 0
	v_readlane_b32 s45, v250, 29
	v_readlane_b32 s46, v250, 30
	v_readlane_b32 s47, v250, 31
	v_readlane_b32 s48, v250, 32
	v_readlane_b32 s49, v250, 33
	v_readlane_b32 s50, v250, 34
	v_readlane_b32 s51, v250, 35
	v_readlane_b32 s52, v250, 36
	v_readlane_b32 s53, v250, 37
	v_readlane_b32 s54, v250, 38
	v_readlane_b32 s55, v250, 39
	v_readlane_b32 s56, v250, 40
	v_readlane_b32 s57, v250, 41
	s_mov_b64 s[4:5], s[58:59]
	s_branch .LBB0_38

.LBB0_69:
	s_add_i32 s24, s19, s92
	s_add_i32 s101, s33, 0xa00
	s_cmp_lt_u32 s33, 0x60
	s_cselect_b32 s101, s101, 0x1a7f
	s_cmp_lg_u32 s100, 0
	s_cselect_b32 s101, -1, s101
	s_mov_b32 s98, 0
	s_cmp_le_i32 s24, s101
	s_cbranch_scc1 .Lp0_join
	s_mov_b32 s98, 1
	s_movk_i32 s24, 0x7fff
	s_cmp_lt_u32 s33, 0x60
	s_cbranch_scc1 .Lp0_join
	s_sub_u32 s99, s33, 0x60
	s_mul_i32 s101, s100, 0x1a0
	s_add_u32 s99, s99, s101
	s_add_u32 s100, s100, 1
	s_cmp_ge_u32 s99, 0x300
	s_cbranch_scc1 .Lp0_join
	s_mul_hi_u32 s101, s99, 0x2aaaaab
	s_mul_i32 s24, s101, 0x60
	s_sub_u32 s24, s99, s24
	s_add_u32 s101, s101, 6
	s_lshl_b32 s101, s101, 9
	s_add_u32 s24, s24, s101
	s_sub_u32 s19, s24, s92
	s_mov_b32 s98, 0
.Lp0_join:
	s_cmp_lg_u32 s98, 0
	s_cselect_b64 s[4:5], -1, 0
	s_and_b64 vcc, exec, s[4:5]
	s_waitcnt vmcnt(3)
	ds_write2_b32 v24, v1, v2 offset0:1 offset1:2
	ds_write2_b32 v24, v0, v3 offset1:3
	s_waitcnt vmcnt(2)
	ds_write2_b32 v26, v4, v5 offset1:1
	ds_write2_b32 v27, v6, v7 offset1:1
	s_waitcnt vmcnt(1)
	ds_write2_b32 v28, v8, v9 offset1:1
	ds_write2_b32 v29, v10, v11 offset1:1
	s_waitcnt vmcnt(0)
	ds_write2_b32 v30, v12, v13 offset1:1
	ds_write2_b32 v31, v14, v15 offset1:1
	s_cbranch_vccnz .LBB0_68
	s_add_i32 s28, s24, 0xffffffa0
	s_cmpk_gt_i32 s24, 0x4ff
	s_cbranch_scc0 .LBB0_76
	s_cmpk_gt_u32 s28, 0x59f
	s_cbranch_scc0 .LBB0_77
	s_cmpk_gt_u32 s28, 0x109f
	s_mov_b64 s[12:13], -1
	s_cbranch_scc0 .LBB0_84
	s_cmpk_gt_u32 s28, 0x161f
	s_cbranch_scc0 .LBB0_81
	s_cmpk_gt_u32 s28, 0x191f
	s_cbranch_scc0 .LBB0_78
	v_readlane_b32 s44, v250, 28
	s_add_i32 s6, s24, 0xffffe680
	v_readlane_b32 s58, v250, 42
	v_readlane_b32 s59, v250, 43
	s_lshr_b32 s25, s6, 4
	v_readlane_b32 s45, v250, 29
	v_readlane_b32 s46, v250, 30
	v_readlane_b32 s47, v250, 31
	v_readlane_b32 s48, v250, 32
	v_readlane_b32 s49, v250, 33
	v_readlane_b32 s50, v250, 34
	v_readlane_b32 s51, v250, 35
	v_readlane_b32 s52, v250, 36
	v_readlane_b32 s53, v250, 37
	v_readlane_b32 s54, v250, 38
	v_readlane_b32 s55, v250, 39
	v_readlane_b32 s56, v250, 40
	v_readlane_b32 s57, v250, 41
	s_mov_b64 s[8:9], s[58:59]
	s_mov_b64 s[10:11], 0x400
	s_mov_b64 s[6:7], s[64:65]
	s_cbranch_execz .LBB0_79
	s_branch .LBB0_80
